# S5 step1 fragment loads prefetched one tile ahead; EpiIn epilogue part loads pipelined with counted vmcnt
# speedup vs baseline: 1.0077x; 1.0077x over previous
.LBB0_219:
	v_lshl_add_u32 v142, s8, 8, v144
	s_and_b32 s9, s7, -4
	s_cmp_eq_u32 s9, 4
	s_cselect_b64 vcc, -1, 0
	s_lshl_b32 s46, s7, 8
	s_ashr_i32 s47, s46, 31
	s_lshl_b64 s[90:91], s[46:47], 1
	v_lshlrev_b32_e32 v140, 6, v142
	global_load_dwordx4 v[148:151], v140, s[54:55] offset:48
	global_load_dwordx4 v[152:155], v140, s[54:55] offset:32
	global_load_dwordx4 v[156:159], v140, s[54:55] offset:16
	global_load_dwordx4 v[160:163], v140, s[54:55]
	v_add_u32_e32 v141, 0x10, v142
	v_lshlrev_b32_e32 v140, 6, v141
	global_load_dwordx4 v[164:167], v140, s[54:55] offset:48
	global_load_dwordx4 v[168:171], v140, s[54:55] offset:32
	global_load_dwordx4 v[172:175], v140, s[54:55] offset:16
	global_load_dwordx4 v[176:179], v140, s[54:55]
	v_add_u32_e32 v141, 0x20, v142
	v_lshlrev_b32_e32 v140, 6, v141
	global_load_dwordx4 v[180:183], v140, s[54:55] offset:48
	global_load_dwordx4 v[184:187], v140, s[54:55] offset:32
	global_load_dwordx4 v[208:211], v140, s[54:55] offset:16
	global_load_dwordx4 v[212:215], v140, s[54:55]
	v_add_u32_e32 v141, 0x30, v142
	v_lshlrev_b32_e32 v140, 6, v141
	global_load_dwordx4 v[228:231], v140, s[54:55] offset:48
	global_load_dwordx4 v[232:235], v140, s[54:55] offset:32
	global_load_dwordx4 v[236:239], v140, s[54:55] offset:16
	global_load_dwordx4 v[240:243], v140, s[54:55]
	v_cndmask_b32_e32 v147, 1.0, v221, vcc
	v_mov_b64_e32 v[246:247], s[82:83]
	v_lshl_add_u64 v[246:247], v[246:247], 0, s[90:91]
	v_lshl_add_u64 v[246:247], v[246:247], 0, s[92:93]
	v_lshl_add_u64 v[246:247], v[246:247], 0, v[194:195]
	s_waitcnt vmcnt(12)
	v_add_f32_e32 v160, v160, v161
	v_add_f32_e32 v162, v162, v163
	v_add_f32_e32 v156, v156, v157
	v_add_f32_e32 v158, v158, v159
	v_add_f32_e32 v152, v152, v153
	v_add_f32_e32 v154, v154, v155
	v_add_f32_e32 v148, v148, v149
	v_add_f32_e32 v150, v150, v151
	v_add_f32_e32 v160, v160, v162
	v_add_f32_e32 v156, v156, v158
	v_add_f32_e32 v152, v152, v154
	v_add_f32_e32 v148, v148, v150
	v_add_f32_e32 v160, v160, v156
	v_add_f32_e32 v160, v160, v152
	v_add_f32_e32 v160, v160, v148
	v_fmamk_f32 v160, v160, 0x3a800000, v189
	v_cmp_gt_f32_e32 vcc, s13, v160
	v_mul_f32_e32 v161, 0x4b800000, v160
	s_nop 0
	v_cndmask_b32_e32 v160, v160, v161, vcc
	v_rsq_f32_e32 v160, v160
	s_nop 0
	v_mul_f32_e32 v161, 0x45800000, v160
	v_cndmask_b32_e32 v160, v160, v161, vcc
	v_mul_f32_e32 v248, v147, v160
	v_mad_i64_i32 v[244:245], s[8:9], v142, s14, v[246:247]
	v_pk_mul_f32 v[124:125], v[124:125], v[248:249] op_sel_hi:[1,0]
	v_pk_mul_f32 v[126:127], v[126:127], v[248:249] op_sel_hi:[1,0]
	v_pk_mul_f32 v[120:121], v[120:121], v[248:249] op_sel_hi:[1,0]
	v_pk_mul_f32 v[122:123], v[122:123], v[248:249] op_sel_hi:[1,0]
	v_cvt_pk_bf16_f32 v124, v124, v125
	v_cvt_pk_bf16_f32 v125, v126, v127
	v_cvt_pk_bf16_f32 v126, v120, v121
	v_cvt_pk_bf16_f32 v127, v122, v123
	global_store_dwordx4 v[244:245], v[124:127], off nt
	v_pk_mul_f32 v[116:117], v[116:117], v[248:249] op_sel_hi:[1,0]
	v_pk_mul_f32 v[118:119], v[118:119], v[248:249] op_sel_hi:[1,0]
	v_pk_mul_f32 v[112:113], v[112:113], v[248:249] op_sel_hi:[1,0]
	v_pk_mul_f32 v[114:115], v[114:115], v[248:249] op_sel_hi:[1,0]
	v_cvt_pk_bf16_f32 v116, v116, v117
	v_cvt_pk_bf16_f32 v117, v118, v119
	v_cvt_pk_bf16_f32 v118, v112, v113
	v_cvt_pk_bf16_f32 v119, v114, v115
	global_store_dwordx4 v[244:245], v[116:119], off offset:256 nt
	v_add_u32_e32 v141, 0x80, v142
	v_lshlrev_b32_e32 v140, 6, v141
	global_load_dwordx4 v[112:115], v140, s[54:55] offset:48
	global_load_dwordx4 v[116:119], v140, s[54:55] offset:32
	global_load_dwordx4 v[120:123], v140, s[54:55] offset:16
	global_load_dwordx4 v[124:127], v140, s[54:55]
	s_waitcnt vmcnt(14)
	v_add_f32_e32 v176, v176, v177
	v_add_f32_e32 v178, v178, v179
	v_add_f32_e32 v172, v172, v173
	v_add_f32_e32 v174, v174, v175
	v_add_f32_e32 v168, v168, v169
	v_add_f32_e32 v170, v170, v171
	v_add_f32_e32 v164, v164, v165
	v_add_f32_e32 v166, v166, v167
	v_add_f32_e32 v176, v176, v178
	v_add_f32_e32 v172, v172, v174
	v_add_f32_e32 v168, v168, v170
	v_add_f32_e32 v164, v164, v166
	v_add_f32_e32 v176, v176, v172
	v_add_f32_e32 v176, v176, v168
	v_add_f32_e32 v176, v176, v164
	v_fmamk_f32 v176, v176, 0x3a800000, v189
	v_cmp_gt_f32_e32 vcc, s13, v176
	v_mul_f32_e32 v177, 0x4b800000, v176
	s_nop 0
	v_cndmask_b32_e32 v176, v176, v177, vcc
	v_rsq_f32_e32 v176, v176
	s_nop 0
	v_mul_f32_e32 v177, 0x45800000, v176
	v_cndmask_b32_e32 v176, v176, v177, vcc
	v_mul_f32_e32 v248, v147, v176
	v_add_u32_e32 v141, 0x10, v142
	v_mad_i64_i32 v[244:245], s[8:9], v141, s14, v[246:247]
	v_pk_mul_f32 v[108:109], v[108:109], v[248:249] op_sel_hi:[1,0]
	v_pk_mul_f32 v[110:111], v[110:111], v[248:249] op_sel_hi:[1,0]
	v_pk_mul_f32 v[104:105], v[104:105], v[248:249] op_sel_hi:[1,0]
	v_pk_mul_f32 v[106:107], v[106:107], v[248:249] op_sel_hi:[1,0]
	v_cvt_pk_bf16_f32 v108, v108, v109
	v_cvt_pk_bf16_f32 v109, v110, v111
	v_cvt_pk_bf16_f32 v110, v104, v105
	v_cvt_pk_bf16_f32 v111, v106, v107
	global_store_dwordx4 v[244:245], v[108:111], off nt
	v_pk_mul_f32 v[100:101], v[100:101], v[248:249] op_sel_hi:[1,0]
	v_pk_mul_f32 v[102:103], v[102:103], v[248:249] op_sel_hi:[1,0]
	v_pk_mul_f32 v[96:97], v[96:97], v[248:249] op_sel_hi:[1,0]
	v_pk_mul_f32 v[98:99], v[98:99], v[248:249] op_sel_hi:[1,0]
	v_cvt_pk_bf16_f32 v100, v100, v101
	v_cvt_pk_bf16_f32 v101, v102, v103
	v_cvt_pk_bf16_f32 v102, v96, v97
	v_cvt_pk_bf16_f32 v103, v98, v99
	global_store_dwordx4 v[244:245], v[100:103], off offset:256 nt
	v_add_u32_e32 v141, 0x90, v142
	v_lshlrev_b32_e32 v140, 6, v141
	global_load_dwordx4 v[96:99], v140, s[54:55] offset:48
	global_load_dwordx4 v[100:103], v140, s[54:55] offset:32
	global_load_dwordx4 v[104:107], v140, s[54:55] offset:16
	global_load_dwordx4 v[108:111], v140, s[54:55]
	s_waitcnt vmcnt(16)
	v_add_f32_e32 v212, v212, v213
	v_add_f32_e32 v214, v214, v215
	v_add_f32_e32 v208, v208, v209
	v_add_f32_e32 v210, v210, v211
	v_add_f32_e32 v184, v184, v185
	v_add_f32_e32 v186, v186, v187
	v_add_f32_e32 v180, v180, v181
	v_add_f32_e32 v182, v182, v183
	v_add_f32_e32 v212, v212, v214
	v_add_f32_e32 v208, v208, v210
	v_add_f32_e32 v184, v184, v186
	v_add_f32_e32 v180, v180, v182
	v_add_f32_e32 v212, v212, v208
	v_add_f32_e32 v212, v212, v184
	v_add_f32_e32 v212, v212, v180
	v_fmamk_f32 v212, v212, 0x3a800000, v189
	v_cmp_gt_f32_e32 vcc, s13, v212
	v_mul_f32_e32 v213, 0x4b800000, v212
	s_nop 0
	v_cndmask_b32_e32 v212, v212, v213, vcc
	v_rsq_f32_e32 v212, v212
	s_nop 0
	v_mul_f32_e32 v213, 0x45800000, v212
	v_cndmask_b32_e32 v212, v212, v213, vcc
	v_mul_f32_e32 v248, v147, v212
	v_add_u32_e32 v141, 0x20, v142
	v_mad_i64_i32 v[244:245], s[8:9], v141, s14, v[246:247]
	v_pk_mul_f32 v[92:93], v[92:93], v[248:249] op_sel_hi:[1,0]
	v_pk_mul_f32 v[94:95], v[94:95], v[248:249] op_sel_hi:[1,0]
	v_pk_mul_f32 v[88:89], v[88:89], v[248:249] op_sel_hi:[1,0]
	v_pk_mul_f32 v[90:91], v[90:91], v[248:249] op_sel_hi:[1,0]
	v_cvt_pk_bf16_f32 v92, v92, v93
	v_cvt_pk_bf16_f32 v93, v94, v95
	v_cvt_pk_bf16_f32 v94, v88, v89
	v_cvt_pk_bf16_f32 v95, v90, v91
	global_store_dwordx4 v[244:245], v[92:95], off nt
	v_pk_mul_f32 v[84:85], v[84:85], v[248:249] op_sel_hi:[1,0]
	v_pk_mul_f32 v[86:87], v[86:87], v[248:249] op_sel_hi:[1,0]
	v_pk_mul_f32 v[80:81], v[80:81], v[248:249] op_sel_hi:[1,0]
	v_pk_mul_f32 v[82:83], v[82:83], v[248:249] op_sel_hi:[1,0]
	v_cvt_pk_bf16_f32 v84, v84, v85
	v_cvt_pk_bf16_f32 v85, v86, v87
	v_cvt_pk_bf16_f32 v86, v80, v81
	v_cvt_pk_bf16_f32 v87, v82, v83
	global_store_dwordx4 v[244:245], v[84:87], off offset:256 nt
	v_add_u32_e32 v141, 0xa0, v142
	v_lshlrev_b32_e32 v140, 6, v141
	global_load_dwordx4 v[80:83], v140, s[54:55] offset:48
	global_load_dwordx4 v[84:87], v140, s[54:55] offset:32
	global_load_dwordx4 v[88:91], v140, s[54:55] offset:16
	global_load_dwordx4 v[92:95], v140, s[54:55]
	s_waitcnt vmcnt(18)
	v_add_f32_e32 v240, v240, v241
	v_add_f32_e32 v242, v242, v243
	v_add_f32_e32 v236, v236, v237
	v_add_f32_e32 v238, v238, v239
	v_add_f32_e32 v232, v232, v233
	v_add_f32_e32 v234, v234, v235
	v_add_f32_e32 v228, v228, v229
	v_add_f32_e32 v230, v230, v231
	v_add_f32_e32 v240, v240, v242
	v_add_f32_e32 v236, v236, v238
	v_add_f32_e32 v232, v232, v234
	v_add_f32_e32 v228, v228, v230
	v_add_f32_e32 v240, v240, v236
	v_add_f32_e32 v240, v240, v232
	v_add_f32_e32 v240, v240, v228
	v_fmamk_f32 v240, v240, 0x3a800000, v189
	v_cmp_gt_f32_e32 vcc, s13, v240
	v_mul_f32_e32 v241, 0x4b800000, v240
	s_nop 0
	v_cndmask_b32_e32 v240, v240, v241, vcc
	v_rsq_f32_e32 v240, v240
	s_nop 0
	v_mul_f32_e32 v241, 0x45800000, v240
	v_cndmask_b32_e32 v240, v240, v241, vcc
	v_mul_f32_e32 v248, v147, v240
	v_add_u32_e32 v141, 0x30, v142
	v_mad_i64_i32 v[244:245], s[8:9], v141, s14, v[246:247]
	v_pk_mul_f32 v[76:77], v[76:77], v[248:249] op_sel_hi:[1,0]
	v_pk_mul_f32 v[78:79], v[78:79], v[248:249] op_sel_hi:[1,0]
	v_pk_mul_f32 v[72:73], v[72:73], v[248:249] op_sel_hi:[1,0]
	v_pk_mul_f32 v[74:75], v[74:75], v[248:249] op_sel_hi:[1,0]
	v_cvt_pk_bf16_f32 v76, v76, v77
	v_cvt_pk_bf16_f32 v77, v78, v79
	v_cvt_pk_bf16_f32 v78, v72, v73
	v_cvt_pk_bf16_f32 v79, v74, v75
	global_store_dwordx4 v[244:245], v[76:79], off nt
	v_pk_mul_f32 v[68:69], v[68:69], v[248:249] op_sel_hi:[1,0]
	v_pk_mul_f32 v[70:71], v[70:71], v[248:249] op_sel_hi:[1,0]
	v_pk_mul_f32 v[64:65], v[64:65], v[248:249] op_sel_hi:[1,0]
	v_pk_mul_f32 v[66:67], v[66:67], v[248:249] op_sel_hi:[1,0]
	v_cvt_pk_bf16_f32 v68, v68, v69
	v_cvt_pk_bf16_f32 v69, v70, v71
	v_cvt_pk_bf16_f32 v70, v64, v65
	v_cvt_pk_bf16_f32 v71, v66, v67
	global_store_dwordx4 v[244:245], v[68:71], off offset:256 nt
	v_add_u32_e32 v141, 0xb0, v142
	v_lshlrev_b32_e32 v140, 6, v141
	global_load_dwordx4 v[64:67], v140, s[54:55] offset:48
	global_load_dwordx4 v[68:71], v140, s[54:55] offset:32
	global_load_dwordx4 v[72:75], v140, s[54:55] offset:16
	global_load_dwordx4 v[76:79], v140, s[54:55]
	s_waitcnt vmcnt(18)
	v_add_f32_e32 v124, v124, v125
	v_add_f32_e32 v126, v126, v127
	v_add_f32_e32 v120, v120, v121
	v_add_f32_e32 v122, v122, v123
	v_add_f32_e32 v116, v116, v117
	v_add_f32_e32 v118, v118, v119
	v_add_f32_e32 v112, v112, v113
	v_add_f32_e32 v114, v114, v115
	v_add_f32_e32 v124, v124, v126
	v_add_f32_e32 v120, v120, v122
	v_add_f32_e32 v116, v116, v118
	v_add_f32_e32 v112, v112, v114
	v_add_f32_e32 v124, v124, v120
	v_add_f32_e32 v124, v124, v116
	v_add_f32_e32 v124, v124, v112
	v_fmamk_f32 v124, v124, 0x3a800000, v189
	v_cmp_gt_f32_e32 vcc, s13, v124
	v_mul_f32_e32 v125, 0x4b800000, v124
	s_nop 0
	v_cndmask_b32_e32 v124, v124, v125, vcc
	v_rsq_f32_e32 v124, v124
	s_nop 0
	v_mul_f32_e32 v125, 0x45800000, v124
	v_cndmask_b32_e32 v124, v124, v125, vcc
	v_mul_f32_e32 v248, v147, v124
	v_add_u32_e32 v141, 0x80, v142
	v_mad_i64_i32 v[244:245], s[8:9], v141, s14, v[246:247]
	v_pk_mul_f32 v[60:61], v[60:61], v[248:249] op_sel_hi:[1,0]
	v_pk_mul_f32 v[62:63], v[62:63], v[248:249] op_sel_hi:[1,0]
	v_pk_mul_f32 v[56:57], v[56:57], v[248:249] op_sel_hi:[1,0]
	v_pk_mul_f32 v[58:59], v[58:59], v[248:249] op_sel_hi:[1,0]
	v_cvt_pk_bf16_f32 v60, v60, v61
	v_cvt_pk_bf16_f32 v61, v62, v63
	v_cvt_pk_bf16_f32 v62, v56, v57
	v_cvt_pk_bf16_f32 v63, v58, v59
	global_store_dwordx4 v[244:245], v[60:63], off nt
	v_pk_mul_f32 v[52:53], v[52:53], v[248:249] op_sel_hi:[1,0]
	v_pk_mul_f32 v[54:55], v[54:55], v[248:249] op_sel_hi:[1,0]
	v_pk_mul_f32 v[48:49], v[48:49], v[248:249] op_sel_hi:[1,0]
	v_pk_mul_f32 v[50:51], v[50:51], v[248:249] op_sel_hi:[1,0]
	v_cvt_pk_bf16_f32 v52, v52, v53
	v_cvt_pk_bf16_f32 v53, v54, v55
	v_cvt_pk_bf16_f32 v54, v48, v49
	v_cvt_pk_bf16_f32 v55, v50, v51
	global_store_dwordx4 v[244:245], v[52:55], off offset:256 nt
	s_waitcnt vmcnt(14)
	v_add_f32_e32 v108, v108, v109
	v_add_f32_e32 v110, v110, v111
	v_add_f32_e32 v104, v104, v105
	v_add_f32_e32 v106, v106, v107
	v_add_f32_e32 v100, v100, v101
	v_add_f32_e32 v102, v102, v103
	v_add_f32_e32 v96, v96, v97
	v_add_f32_e32 v98, v98, v99
	v_add_f32_e32 v108, v108, v110
	v_add_f32_e32 v104, v104, v106
	v_add_f32_e32 v100, v100, v102
	v_add_f32_e32 v96, v96, v98
	v_add_f32_e32 v108, v108, v104
	v_add_f32_e32 v108, v108, v100
	v_add_f32_e32 v108, v108, v96
	v_fmamk_f32 v108, v108, 0x3a800000, v189
	v_cmp_gt_f32_e32 vcc, s13, v108
	v_mul_f32_e32 v109, 0x4b800000, v108
	s_nop 0
	v_cndmask_b32_e32 v108, v108, v109, vcc
	v_rsq_f32_e32 v108, v108
	s_nop 0
	v_mul_f32_e32 v109, 0x45800000, v108
	v_cndmask_b32_e32 v108, v108, v109, vcc
	v_mul_f32_e32 v248, v147, v108
	v_add_u32_e32 v141, 0x90, v142
	v_mad_i64_i32 v[244:245], s[8:9], v141, s14, v[246:247]
	v_pk_mul_f32 v[44:45], v[44:45], v[248:249] op_sel_hi:[1,0]
	v_pk_mul_f32 v[46:47], v[46:47], v[248:249] op_sel_hi:[1,0]
	v_pk_mul_f32 v[40:41], v[40:41], v[248:249] op_sel_hi:[1,0]
	v_pk_mul_f32 v[42:43], v[42:43], v[248:249] op_sel_hi:[1,0]
	v_cvt_pk_bf16_f32 v44, v44, v45
	v_cvt_pk_bf16_f32 v45, v46, v47
	v_cvt_pk_bf16_f32 v46, v40, v41
	v_cvt_pk_bf16_f32 v47, v42, v43
	global_store_dwordx4 v[244:245], v[44:47], off nt
	v_pk_mul_f32 v[36:37], v[36:37], v[248:249] op_sel_hi:[1,0]
	v_pk_mul_f32 v[38:39], v[38:39], v[248:249] op_sel_hi:[1,0]
	v_pk_mul_f32 v[32:33], v[32:33], v[248:249] op_sel_hi:[1,0]
	v_pk_mul_f32 v[34:35], v[34:35], v[248:249] op_sel_hi:[1,0]
	v_cvt_pk_bf16_f32 v36, v36, v37
	v_cvt_pk_bf16_f32 v37, v38, v39
	v_cvt_pk_bf16_f32 v38, v32, v33
	v_cvt_pk_bf16_f32 v39, v34, v35
	global_store_dwordx4 v[244:245], v[36:39], off offset:256 nt
	s_waitcnt vmcnt(10)
	v_add_f32_e32 v92, v92, v93
	v_add_f32_e32 v94, v94, v95
	v_add_f32_e32 v88, v88, v89
	v_add_f32_e32 v90, v90, v91
	v_add_f32_e32 v84, v84, v85
	v_add_f32_e32 v86, v86, v87
	v_add_f32_e32 v80, v80, v81
	v_add_f32_e32 v82, v82, v83
	v_add_f32_e32 v92, v92, v94
	v_add_f32_e32 v88, v88, v90
	v_add_f32_e32 v84, v84, v86
	v_add_f32_e32 v80, v80, v82
	v_add_f32_e32 v92, v92, v88
	v_add_f32_e32 v92, v92, v84
	v_add_f32_e32 v92, v92, v80
	v_fmamk_f32 v92, v92, 0x3a800000, v189
	v_cmp_gt_f32_e32 vcc, s13, v92
	v_mul_f32_e32 v93, 0x4b800000, v92
	s_nop 0
	v_cndmask_b32_e32 v92, v92, v93, vcc
	v_rsq_f32_e32 v92, v92
	s_nop 0
	v_mul_f32_e32 v93, 0x45800000, v92
	v_cndmask_b32_e32 v92, v92, v93, vcc
	v_mul_f32_e32 v248, v147, v92
	v_add_u32_e32 v141, 0xa0, v142
	v_mad_i64_i32 v[244:245], s[8:9], v141, s14, v[246:247]
	v_pk_mul_f32 v[28:29], v[28:29], v[248:249] op_sel_hi:[1,0]
	v_pk_mul_f32 v[30:31], v[30:31], v[248:249] op_sel_hi:[1,0]
	v_pk_mul_f32 v[24:25], v[24:25], v[248:249] op_sel_hi:[1,0]
	v_pk_mul_f32 v[26:27], v[26:27], v[248:249] op_sel_hi:[1,0]
	v_cvt_pk_bf16_f32 v28, v28, v29
	v_cvt_pk_bf16_f32 v29, v30, v31
	v_cvt_pk_bf16_f32 v30, v24, v25
	v_cvt_pk_bf16_f32 v31, v26, v27
	global_store_dwordx4 v[244:245], v[28:31], off nt
	v_pk_mul_f32 v[20:21], v[20:21], v[248:249] op_sel_hi:[1,0]
	v_pk_mul_f32 v[22:23], v[22:23], v[248:249] op_sel_hi:[1,0]
	v_pk_mul_f32 v[16:17], v[16:17], v[248:249] op_sel_hi:[1,0]
	v_pk_mul_f32 v[18:19], v[18:19], v[248:249] op_sel_hi:[1,0]
	v_cvt_pk_bf16_f32 v20, v20, v21
	v_cvt_pk_bf16_f32 v21, v22, v23
	v_cvt_pk_bf16_f32 v22, v16, v17
	v_cvt_pk_bf16_f32 v23, v18, v19
	global_store_dwordx4 v[244:245], v[20:23], off offset:256 nt
	s_waitcnt vmcnt(6)
	v_add_f32_e32 v76, v76, v77
	v_add_f32_e32 v78, v78, v79
	v_add_f32_e32 v72, v72, v73
	v_add_f32_e32 v74, v74, v75
	v_add_f32_e32 v68, v68, v69
	v_add_f32_e32 v70, v70, v71
	v_add_f32_e32 v64, v64, v65
	v_add_f32_e32 v66, v66, v67
	v_add_f32_e32 v76, v76, v78
	v_add_f32_e32 v72, v72, v74
	v_add_f32_e32 v68, v68, v70
	v_add_f32_e32 v64, v64, v66
	v_add_f32_e32 v76, v76, v72
	v_add_f32_e32 v76, v76, v68
	v_add_f32_e32 v76, v76, v64
	v_fmamk_f32 v76, v76, 0x3a800000, v189
	v_cmp_gt_f32_e32 vcc, s13, v76
	v_mul_f32_e32 v77, 0x4b800000, v76
	s_nop 0
	v_cndmask_b32_e32 v76, v76, v77, vcc
	v_rsq_f32_e32 v76, v76
	s_nop 0
	v_mul_f32_e32 v77, 0x45800000, v76
	v_cndmask_b32_e32 v76, v76, v77, vcc
	v_mul_f32_e32 v248, v147, v76
	v_add_u32_e32 v141, 0xb0, v142
	v_mad_i64_i32 v[244:245], s[8:9], v141, s14, v[246:247]
	v_pk_mul_f32 v[12:13], v[12:13], v[248:249] op_sel_hi:[1,0]
	v_pk_mul_f32 v[14:15], v[14:15], v[248:249] op_sel_hi:[1,0]
	v_pk_mul_f32 v[8:9], v[8:9], v[248:249] op_sel_hi:[1,0]
	v_pk_mul_f32 v[10:11], v[10:11], v[248:249] op_sel_hi:[1,0]
	v_cvt_pk_bf16_f32 v12, v12, v13
	v_cvt_pk_bf16_f32 v13, v14, v15
	v_cvt_pk_bf16_f32 v14, v8, v9
	v_cvt_pk_bf16_f32 v15, v10, v11
	global_store_dwordx4 v[244:245], v[12:15], off nt
	v_pk_mul_f32 v[4:5], v[4:5], v[248:249] op_sel_hi:[1,0]
	v_pk_mul_f32 v[6:7], v[6:7], v[248:249] op_sel_hi:[1,0]
	v_pk_mul_f32 v[0:1], v[0:1], v[248:249] op_sel_hi:[1,0]
	v_pk_mul_f32 v[2:3], v[2:3], v[248:249] op_sel_hi:[1,0]
	v_cvt_pk_bf16_f32 v4, v4, v5
	v_cvt_pk_bf16_f32 v5, v6, v7
	v_cvt_pk_bf16_f32 v6, v0, v1
	v_cvt_pk_bf16_f32 v7, v2, v3
	s_mov_b64 s[90:91], -1
	s_andn2_b64 vcc, exec, s[36:37]
	global_store_dwordx4 v[244:245], v[4:7], off offset:256 nt
	s_cbranch_vccnz .LBB0_212
	s_andn2_b64 vcc, exec, s[0:1]
	s_cbranch_vccnz .LBB0_211
	s_barrier
	s_branch .LBB0_211

.LBB0_294:
	s_ashr_i32 s16, s12, 5
	v_mov_b32_e32 v104, v217
	s_ashr_i32 s17, s16, 31
	v_and_b32_e32 v128, 15, v104
	v_ashrrev_i32_e32 v182, 5, v104
	s_lshl_b64 s[36:37], s[16:17], 12
	v_ashrrev_i32_e32 v183, 31, v182
	v_lshl_or_b32 v126, v128, 4, s18
	v_lshl_add_u64 v[32:33], s[36:37], 0, v[182:183]
	v_ashrrev_i32_e32 v127, 31, v126
	s_and_b32 s0, s11, 31
	v_lshl_add_u64 v[0:1], v[32:33], 0, v[126:127]
	v_mov_b64_e32 v[34:35], s[82:83]
	s_add_i32 s92, s3, s0
	s_and_b32 s8, s12, 31
	v_mad_u64_u32 v[2:3], s[16:17], v0, s14, v[34:35]
	s_lshl_b64 s[0:1], s[92:93], 16
	v_mad_i32_i24 v3, v1, s14, v3
	s_lshl_b32 s92, s8, 5
	v_and_b32_e32 v194, 16, v104
	v_lshl_add_u64 v[0:1], v[2:3], 0, s[92:93]
	v_lshl_add_u64 v[24:25], v[0:1], 0, v[194:195]
	v_add_co_u32_e32 v0, vcc, s15, v24
	v_or_b32_e32 v124, 0x100, v126
	s_nop 0
	v_addc_co_u32_e32 v1, vcc, 0, v25, vcc
	v_add_co_u32_e32 v4, vcc, s95, v24
	v_ashrrev_i32_e32 v125, 31, v124
	s_nop 0
	v_addc_co_u32_e32 v5, vcc, 0, v25, vcc
	v_add_co_u32_e32 v8, vcc, s47, v24
	v_lshl_add_u64 v[32:33], v[32:33], 0, v[124:125]
	s_nop 0
	v_addc_co_u32_e32 v9, vcc, 0, v25, vcc
	v_add_co_u32_e32 v12, vcc, s60, v24
	v_mad_u64_u32 v[34:35], s[16:17], v32, s14, v[34:35]
	s_nop 0
	v_addc_co_u32_e32 v13, vcc, 0, v25, vcc
	v_add_co_u32_e32 v16, vcc, s64, v24
	v_mad_i32_i24 v35, v33, s14, v35
	s_nop 0
	v_addc_co_u32_e32 v17, vcc, 0, v25, vcc
	v_add_co_u32_e32 v20, vcc, s46, v24
	v_lshl_add_u64 v[32:33], v[34:35], 0, s[92:93]
	s_nop 0
	v_addc_co_u32_e32 v21, vcc, 0, v25, vcc
	v_add_co_u32_e32 v26, vcc, s65, v24
	v_lshl_add_u64 v[56:57], v[32:33], 0, v[194:195]
	s_nop 0
	v_addc_co_u32_e32 v27, vcc, 0, v25, vcc
	v_add_co_u32_e32 v28, vcc, s66, v24
	global_load_dwordx4 v[0:3], v[0:1], off
	s_nop 0
	global_load_dwordx4 v[4:7], v[4:5], off offset:2048
	v_addc_co_u32_e32 v29, vcc, 0, v25, vcc
	v_add_co_u32_e32 v32, vcc, s15, v56
	global_load_dwordx4 v[8:11], v[8:9], off
	s_nop 0
	global_load_dwordx4 v[12:15], v[12:13], off offset:2048
	v_addc_co_u32_e32 v33, vcc, 0, v57, vcc
	v_add_co_u32_e32 v36, vcc, s95, v56
	global_load_dwordx4 v[16:19], v[16:17], off
	s_nop 0
	global_load_dwordx4 v[20:23], v[20:21], off offset:2048
	v_addc_co_u32_e32 v37, vcc, 0, v57, vcc
	v_add_co_u32_e32 v40, vcc, s47, v56
	global_load_dwordx4 v[24:27], v[26:27], off
	s_nop 0
	global_load_dwordx4 v[28:31], v[28:29], off offset:2048
	v_addc_co_u32_e32 v41, vcc, 0, v57, vcc
	v_add_co_u32_e32 v44, vcc, s60, v56
	global_load_dwordx4 v[32:35], v[32:33], off
	s_nop 0
	global_load_dwordx4 v[36:39], v[36:37], off offset:2048
	v_addc_co_u32_e32 v45, vcc, 0, v57, vcc
	v_add_co_u32_e32 v48, vcc, s64, v56
	global_load_dwordx4 v[40:43], v[40:41], off
	s_nop 0
	global_load_dwordx4 v[44:47], v[44:45], off offset:2048
	v_addc_co_u32_e32 v49, vcc, 0, v57, vcc
	v_add_co_u32_e32 v52, vcc, s46, v56
	s_waitcnt vmcnt(12)
	v_ashrrev_i32_e32 v66, 4, v104
	v_addc_co_u32_e32 v53, vcc, 0, v57, vcc
	v_add_co_u32_e32 v58, vcc, s65, v56
	global_load_dwordx4 v[48:51], v[48:49], off
	s_nop 0
	global_load_dwordx4 v[52:55], v[52:53], off offset:2048
	v_addc_co_u32_e32 v59, vcc, 0, v57, vcc
	v_add_co_u32_e32 v56, vcc, 0x27000, v56
	v_lshlrev_b32_e32 v64, 3, v66
	s_nop 0
	v_addc_co_u32_e32 v57, vcc, 0, v57, vcc
	global_load_dwordx4 v[60:63], v[58:59], off
	s_nop 0
	global_load_dwordx4 v[56:59], v[56:57], off offset:2048
	v_lshlrev_b32_e32 v129, 9, v128
	v_ashrrev_i32_e32 v65, 31, v64
	v_or_b32_e32 v68, s0, v129
	v_mov_b32_e32 v69, s1
	v_and_b32_e32 v183, -16, v104
	v_lshl_add_u64 v[64:65], v[64:65], 1, v[68:69]
	s_lshl_b32 s7, s8, 4
	v_lshlrev_b32_e32 v180, 2, v66
	v_add3_u32 v66, s10, v129, v183
	v_lshl_add_u64 v[64:65], s[82:83], 0, v[64:65]
	s_mov_b64 s[0:1], 0
	v_add_co_u32_e32 v82, vcc, 0x1f680000, v64
	s_nop 1
	v_addc_co_u32_e32 v83, vcc, 0, v65, vcc
	global_load_dwordx4 v[84:87], v[82:83], off
	global_load_dwordx4 v[88:91], v[82:83], off offset:64
	global_load_dwordx4 v[92:95], v[82:83], off offset:128
	global_load_dwordx4 v[96:99], v[82:83], off offset:192
	global_load_dwordx4 v[108:111], v[82:83], off offset:256
	global_load_dwordx4 v[112:115], v[82:83], off offset:320
	global_load_dwordx4 v[116:119], v[82:83], off offset:384
	global_load_dwordx4 v[120:123], v[82:83], off offset:448
.LBB0_295:
	v_add_co_u32_e32 v80, vcc, 0x2000, v82
	s_nop 1
	v_addc_co_u32_e32 v81, vcc, 0, v83, vcc
	global_load_dwordx4 v[132:135], v[80:81], off
	global_load_dwordx4 v[136:139], v[80:81], off offset:64
	global_load_dwordx4 v[140:143], v[80:81], off offset:128
	global_load_dwordx4 v[144:147], v[80:81], off offset:192
	global_load_dwordx4 v[148:151], v[80:81], off offset:256
	global_load_dwordx4 v[152:155], v[80:81], off offset:320
	global_load_dwordx4 v[156:159], v[80:81], off offset:384
	global_load_dwordx4 v[160:163], v[80:81], off offset:448
	s_add_u32 s0, s0, 0x4000
	s_addc_u32 s1, s1, 0
	s_waitcnt vmcnt(8)
	v_mfma_f32_16x16x32_bf16 v[72:75], v[84:87], v[0:3], 0
	v_mfma_f32_16x16x32_bf16 v[76:79], v[84:87], v[32:35], 0
	v_mfma_f32_16x16x32_bf16 v[72:75], v[88:91], v[4:7], v[72:75]
	v_mfma_f32_16x16x32_bf16 v[76:79], v[88:91], v[36:39], v[76:79]
	v_mfma_f32_16x16x32_bf16 v[72:75], v[92:95], v[8:11], v[72:75]
	v_mfma_f32_16x16x32_bf16 v[76:79], v[92:95], v[40:43], v[76:79]
	v_mfma_f32_16x16x32_bf16 v[72:75], v[96:99], v[12:15], v[72:75]
	v_mfma_f32_16x16x32_bf16 v[76:79], v[96:99], v[44:47], v[76:79]
	v_mfma_f32_16x16x32_bf16 v[72:75], v[108:111], v[16:19], v[72:75]
	v_mfma_f32_16x16x32_bf16 v[76:79], v[108:111], v[48:51], v[76:79]
	v_mfma_f32_16x16x32_bf16 v[72:75], v[112:115], v[20:23], v[72:75]
	v_mfma_f32_16x16x32_bf16 v[76:79], v[112:115], v[52:55], v[76:79]
	v_mfma_f32_16x16x32_bf16 v[72:75], v[116:119], v[24:27], v[72:75]
	v_mfma_f32_16x16x32_bf16 v[76:79], v[116:119], v[60:63], v[76:79]
	v_mfma_f32_16x16x32_bf16 v[72:75], v[120:123], v[28:31], v[72:75]
	v_mfma_f32_16x16x32_bf16 v[76:79], v[120:123], v[56:59], v[76:79]
	s_cmp_lg_u32 s0, 0x10000
	s_cbranch_scc0 .Ls5s1_last
	v_add_co_u32_e32 v82, vcc, 0x4000, v82
	s_nop 1
	v_addc_co_u32_e32 v83, vcc, 0, v83, vcc
	global_load_dwordx4 v[84:87], v[82:83], off
	global_load_dwordx4 v[88:91], v[82:83], off offset:64
	global_load_dwordx4 v[92:95], v[82:83], off offset:128
	global_load_dwordx4 v[96:99], v[82:83], off offset:192
	global_load_dwordx4 v[108:111], v[82:83], off offset:256
	global_load_dwordx4 v[112:115], v[82:83], off offset:320
	global_load_dwordx4 v[116:119], v[82:83], off offset:384
	global_load_dwordx4 v[120:123], v[82:83], off offset:448
	ds_write_b128 v66, v[72:75]
	ds_write_b128 v66, v[76:79] offset:8192
	s_waitcnt vmcnt(8)
	s_branch .Ls5s1_second
.Ls5s1_last:
	s_nop 7
	ds_write_b128 v66, v[72:75]
	ds_write_b128 v66, v[76:79] offset:8192
	s_waitcnt vmcnt(0)
.Ls5s1_second:
	v_mfma_f32_16x16x32_bf16 v[72:75], v[132:135], v[0:3], 0
	v_mfma_f32_16x16x32_bf16 v[76:79], v[132:135], v[32:35], 0
	v_mfma_f32_16x16x32_bf16 v[72:75], v[136:139], v[4:7], v[72:75]
	v_mfma_f32_16x16x32_bf16 v[76:79], v[136:139], v[36:39], v[76:79]
	v_mfma_f32_16x16x32_bf16 v[72:75], v[140:143], v[8:11], v[72:75]
	v_mfma_f32_16x16x32_bf16 v[76:79], v[140:143], v[40:43], v[76:79]
	v_mfma_f32_16x16x32_bf16 v[72:75], v[144:147], v[12:15], v[72:75]
	v_mfma_f32_16x16x32_bf16 v[76:79], v[144:147], v[44:47], v[76:79]
	v_mfma_f32_16x16x32_bf16 v[72:75], v[148:151], v[16:19], v[72:75]
	v_mfma_f32_16x16x32_bf16 v[76:79], v[148:151], v[48:51], v[76:79]
	v_mfma_f32_16x16x32_bf16 v[72:75], v[152:155], v[20:23], v[72:75]
	v_mfma_f32_16x16x32_bf16 v[76:79], v[152:155], v[52:55], v[76:79]
	v_mfma_f32_16x16x32_bf16 v[72:75], v[156:159], v[24:27], v[72:75]
	v_mfma_f32_16x16x32_bf16 v[76:79], v[156:159], v[60:63], v[76:79]
	v_mfma_f32_16x16x32_bf16 v[72:75], v[160:163], v[28:31], v[72:75]
	v_mfma_f32_16x16x32_bf16 v[76:79], v[160:163], v[56:59], v[76:79]
	s_nop 7
	ds_write_b128 v66, v[72:75] offset:64
	ds_write_b128 v66, v[76:79] offset:8256
	v_add_u32_e32 v66, 0x80, v66
	s_cmp_lg_u32 s0, 0x10000
	s_cbranch_scc1 .LBB0_295
	s_or_b32 s92, s8, s3
	s_lshl_b64 s[0:1], s[92:93], 13
	s_add_u32 s0, s56, s0
	s_addc_u32 s1, s57, s1
	s_lshl_b64 s[8:9], s[92:93], 16
	v_add_u32_e32 v130, s33, v104
	s_add_u32 s8, s58, s8
	v_lshlrev_b32_e32 v96, 3, v130
	v_lshlrev_b32_e32 v64, 4, v104
	s_addc_u32 s9, s59, s9
	v_and_b32_e32 v100, 0xf0, v64
	v_mov_b32_e32 v101, v195
	v_and_b32_e32 v90, 0xffffff80, v96
	v_lshl_add_u64 v[88:89], s[8:9], 0, v[100:101]
	v_ashrrev_i32_e32 v91, 31, v90
	v_lshl_add_u64 v[64:65], v[90:91], 1, v[88:89]
	v_add_u32_e32 v66, 0x1000, v90
	v_add_u32_e32 v72, 0x2000, v90
	v_add_u32_e32 v74, 0x3000, v90
	v_add_u32_e32 v80, 0x4000, v90
	v_add_u32_e32 v82, 0x5000, v90
	v_add_u32_e32 v92, 0x6000, v90
	v_add_u32_e32 v90, 0x7000, v90
	v_ashrrev_i32_e32 v67, 31, v66
	v_ashrrev_i32_e32 v73, 31, v72
	v_ashrrev_i32_e32 v75, 31, v74
	v_ashrrev_i32_e32 v81, 31, v80
	v_ashrrev_i32_e32 v83, 31, v82
	v_ashrrev_i32_e32 v93, 31, v92
	v_ashrrev_i32_e32 v91, 31, v90
	v_ashrrev_i32_e32 v97, 31, v96
	v_lshl_add_u64 v[68:69], v[66:67], 1, v[88:89]
	v_lshl_add_u64 v[72:73], v[72:73], 1, v[88:89]
	v_lshl_add_u64 v[76:77], v[74:75], 1, v[88:89]
	v_lshl_add_u64 v[80:81], v[80:81], 1, v[88:89]
	v_lshl_add_u64 v[82:83], v[82:83], 1, v[88:89]
	v_lshl_add_u64 v[92:93], v[92:93], 1, v[88:89]
	v_lshl_add_u64 v[88:89], v[90:91], 1, v[88:89]
	v_lshl_add_u64 v[96:97], v[96:97], 1, s[0:1]
	s_waitcnt lgkmcnt(0)
	s_barrier
	global_load_dwordx4 v[64:67], v[64:65], off
	s_nop 0
	global_load_dwordx4 v[68:71], v[68:69], off
	s_nop 0
	global_load_dwordx4 v[72:75], v[72:73], off
	s_nop 0
	global_load_dwordx4 v[76:79], v[76:77], off
	s_nop 0
	global_load_dwordx4 v[84:87], v[80:81], off
	s_nop 0
	global_load_dwordx4 v[80:83], v[82:83], off
	s_nop 0
	global_load_dwordx4 v[92:95], v[92:93], off
	s_nop 0
	global_load_dwordx4 v[88:91], v[88:89], off
	s_andn2_b64 vcc, exec, s[40:41]
	global_load_dwordx4 v[96:99], v[96:97], off
	s_cbranch_vccnz .LBB0_299
	s_lshl_b32 s92, s92, 7
	s_lshl_b64 s[0:1], s[92:93], 2
	s_add_u32 s0, s34, s0
	v_lshlrev_b32_e32 v112, 1, v104
	s_addc_u32 s1, s35, s1
	v_ashrrev_i32_e32 v113, 31, v112
	v_lshl_add_u64 v[102:103], v[112:113], 2, s[0:1]
	global_load_dwordx2 v[102:103], v[102:103], off
	v_lshl_add_u32 v101, v104, 2, 0
	ds_read2st64_b32 v[120:121], v101 offset1:1
	ds_read2st64_b32 v[118:119], v101 offset0:2 offset1:3
	ds_read2st64_b32 v[110:111], v101 offset0:4 offset1:5
	ds_read2st64_b32 v[132:133], v101 offset0:6 offset1:7
	ds_read2st64_b32 v[104:105], v101 offset0:8 offset1:9
	ds_read2st64_b32 v[114:115], v101 offset0:10 offset1:11
	ds_read2st64_b32 v[106:107], v101 offset0:12 offset1:13
	ds_read2st64_b32 v[108:109], v101 offset0:14 offset1:15
	v_mov_b32_e32 v122, 0
	s_mov_b32 s0, 0
	v_sub_u32_e32 v131, v101, v112
	v_mov_b32_e32 v123, v122
	s_waitcnt lgkmcnt(2)
	v_mov_b32_e32 v112, v115
	v_mov_b32_e32 v113, v114
	v_mov_b32_e32 v116, v133
	v_mov_b32_e32 v117, v132
	s_waitcnt vmcnt(0)
	v_pk_mov_b32 v[114:115], v[102:103], v[102:103] op_sel:[1,0]

.LBB0_829:
	s_and_b32 s16, s12, 15
	s_ashr_i32 s8, s12, 7
	s_xor_b32 s34, s16, 31
	s_lshl_b32 s0, s34, 7
	s_ashr_i32 s9, s8, 31
	v_mov_b32_e32 v233, v216
	s_lshl_b64 s[74:75], s[8:9], 12
	s_or_b32 s1, s0, s6
	s_or_b32 s7, s74, s1
	v_and_b32_e32 v214, 31, v233
	v_or_b32_e32 v0, s7, v214
	v_mov_b64_e32 v[38:39], s[82:83]
	s_lshl_b32 s1, s12, 3
	v_mad_u64_u32 v[0:1], s[38:39], v0, s14, v[38:39]
	s_and_b32 s46, s1, 0x380
	v_mad_i32_i24 v1, s75, v225, v1
	s_lshl_b32 s92, s46, 1
	v_readlane_b32 s1, v254, 36
	v_bfe_u32 v215, v233, 5, 1
	v_lshl_add_u64 v[0:1], v[0:1], 0, s[92:93]
	s_lshl_b32 s64, s1, 1
	s_mov_b32 s65, s93
	v_lshl_add_u64 v[0:1], v[0:1], 0, s[64:65]
	v_lshlrev_b32_e32 v194, 4, v215
	v_lshl_add_u64 v[0:1], v[0:1], 0, v[194:195]
	global_load_dwordx4 v[160:163], v[0:1], off offset:2048
	global_load_dwordx4 v[164:167], v[0:1], off offset:2080
	global_load_dwordx4 v[168:171], v[0:1], off offset:2112
	global_load_dwordx4 v[172:175], v[0:1], off offset:2144
	v_lshrrev_b32_e32 v0, 1, v233
	v_bitop3_b32 v0, v215, v0, 7 bitop3:0x78
	v_mov_b32_e32 v1, v233
	v_lshlrev_b32_e32 v228, 4, v0
	v_lshlrev_b32_e32 v227, 7, v214
	v_ashrrev_i32_e32 v0, 3, v1
	v_lshrrev_b32_e32 v2, 4, v1
	v_xor_b32_e32 v6, v2, v1
	v_ashrrev_i32_e32 v1, 31, v0
	v_readlane_b32 s1, v254, 37
	v_lshl_add_u64 v[2:3], s[74:75], 0, v[0:1]
	v_mad_u64_u32 v[4:5], s[38:39], v2, s14, v[38:39]
	v_or_b32_e32 v8, s1, v227
	s_lshl_b32 s1, s8, 10
	v_mad_i32_i24 v5, v3, s14, v5
	v_lshlrev_b32_e32 v1, 4, v6
	s_or_b32 s18, s46, s1
	v_lshl_add_u64 v[2:3], v[4:5], 0, s[92:93]
	v_and_b32_e32 v194, 0x70, v1
	v_add_u32_e32 v0, s18, v0
	v_lshl_add_u64 v[2:3], v[2:3], 0, v[194:195]
	v_ashrrev_i32_e32 v1, 31, v0
	s_mov_b32 m0, s5
	v_lshl_add_u64 v[4:5], v[2:3], 0, s[30:31]
	v_lshlrev_b64 v[0:1], 13, v[0:1]
	s_add_i32 s47, s5, 0x2000
	v_lshl_add_u64 v[0:1], s[66:67], 0, v[0:1]
	global_load_lds_dwordx4 v[4:5], off
	v_lshl_add_u64 v[2:3], v[2:3], 0, s[42:43]
	s_mov_b32 m0, s47
	s_add_i32 s71, s5, 0x4000
	v_lshl_add_u64 v[0:1], v[0:1], 0, v[194:195]
	global_load_lds_dwordx4 v[2:3], off
	s_mov_b32 m0, s71
	s_mov_b64 s[8:9], 0x80000
	s_add_i32 s90, s5, 0x6000
	global_load_lds_dwordx4 v[0:1], off
	v_lshl_add_u64 v[0:1], v[0:1], 0, s[8:9]
	s_mov_b32 m0, s90
	s_add_i32 s91, s5, 0x8000
	global_load_lds_dwordx4 v[0:1], off
	v_mov_b32_e32 v1, v233
	s_mov_b32 s84, s94
	v_ashrrev_i32_e32 v0, 3, v1
	v_lshrrev_b32_e32 v2, 4, v1
	v_xor_b32_e32 v6, v2, v1
	v_ashrrev_i32_e32 v1, 31, v0
	v_lshl_add_u64 v[2:3], s[74:75], 0, v[0:1]
	v_mad_u64_u32 v[4:5], s[8:9], v2, s14, v[38:39]
	v_mad_i32_i24 v5, v3, s14, v5
	v_lshlrev_b32_e32 v1, 4, v6
	v_add_u32_e32 v0, s18, v0
	v_lshl_add_u64 v[2:3], v[4:5], 0, s[92:93]
	v_and_b32_e32 v194, 0x70, v1
	v_ashrrev_i32_e32 v1, 31, v0
	v_lshl_add_u64 v[2:3], v[2:3], 0, v[194:195]
	s_mov_b64 s[8:9], 0xb1c00
	v_lshlrev_b64 v[0:1], 13, v[0:1]
	v_lshl_add_u64 v[4:5], v[2:3], 0, s[8:9]
	v_lshl_add_u64 v[0:1], s[66:67], 0, v[0:1]
	s_mov_b32 m0, s91
	s_mov_b64 s[8:9], 0xb1c80
	s_add_i32 s94, s5, 0xa000
	v_lshl_add_u64 v[0:1], v[0:1], 0, v[194:195]
	global_load_lds_dwordx4 v[4:5], off
	v_lshl_add_u64 v[2:3], v[2:3], 0, s[8:9]
	s_mov_b32 m0, s94
	s_add_i32 s95, s5, 0xc000
	v_lshl_add_u64 v[6:7], v[0:1], 0, s[48:49]
	global_load_lds_dwordx4 v[2:3], off
	s_mov_b32 m0, s95
	s_add_i32 s72, s5, 0xe000
	v_add_u32_e32 v235, 0, v8
	global_load_lds_dwordx4 v[6:7], off
	v_lshl_add_u64 v[0:1], v[0:1], 0, s[96:97]
	s_mov_b32 m0, s72
	v_add_u32_e32 v40, v235, v228
	global_load_lds_dwordx4 v[0:1], off
	s_waitcnt vmcnt(0)
	s_waitcnt lgkmcnt(0)
	s_barrier
	ds_read_b128 v[0:3], v40
	ds_read_b128 v[18:21], v40 offset:4096
	s_waitcnt lgkmcnt(1)
	v_mfma_f32_32x32x16_bf16 v[2:17], v[0:3], v[160:163], 0
	v_bfe_u32 v0, v233, 1, 3
	v_bitop3_b32 v1, v215, v0, 2 bitop3:0x36
	v_lshlrev_b32_e32 v231, 4, v1
	v_add_u32_e32 v41, v235, v231
	ds_read_b128 v[34:37], v41
	v_bitop3_b32 v1, v215, v0, 4 bitop3:0x36
	v_lshlrev_b32_e32 v230, 4, v1
	s_waitcnt lgkmcnt(0)
	v_mfma_f32_32x32x16_bf16 v[2:17], v[34:37], v[164:167], v[2:17]
	ds_read_b128 v[34:37], v41 offset:4096
	v_add_u32_e32 v42, v235, v230
	v_bitop3_b32 v0, v215, v0, 6 bitop3:0x36
	v_lshlrev_b32_e32 v229, 4, v0
	v_add_u32_e32 v62, v235, v229
	v_mov_b32_e32 v1, v233
	s_add_i32 s45, s5, 0x10000
	v_mfma_f32_32x32x16_bf16 v[18:33], v[18:21], v[160:163], 0
	s_mov_b32 m0, s45
	s_add_i32 s73, s5, 0x12000
	s_add_i32 s89, s5, 0x14000
	s_add_i32 s60, s5, 0x16000
	s_lshl_b32 s35, s34, 1
	s_mov_b32 s17, 0xf149f2ca
	v_and_b32_e32 v234, 63, v233
	s_waitcnt lgkmcnt(0)
	v_mfma_f32_32x32x16_bf16 v[18:33], v[34:37], v[164:167], v[18:33]
	ds_read_b128 v[34:37], v42
	s_mov_b32 s65, s75
	s_mov_b32 s10, 2
	v_or_b32_e32 v236, s6, v214
	s_mov_b32 s78, 0x10000
	s_mov_b64 s[38:39], 0
	s_waitcnt lgkmcnt(0)
	v_mfma_f32_32x32x16_bf16 v[2:17], v[34:37], v[168:171], v[2:17]
	ds_read_b128 v[34:37], v42 offset:4096
	s_waitcnt lgkmcnt(0)
	v_mfma_f32_32x32x16_bf16 v[18:33], v[34:37], v[168:171], v[18:33]
	ds_read_b128 v[34:37], v62
	s_waitcnt lgkmcnt(0)
	v_mfma_f32_32x32x16_bf16 v[2:17], v[34:37], v[172:175], v[2:17]
	ds_read_b128 v[34:37], v62 offset:4096
	s_waitcnt lgkmcnt(0)
	v_mfma_f32_32x32x16_bf16 v[18:33], v[34:37], v[172:175], v[18:33]
	s_nop 15
	s_nop 7
	s_nop 0
	v_ashrrev_i32_e32 v0, 3, v1
	v_lshrrev_b32_e32 v34, 4, v1
	v_xor_b32_e32 v43, v34, v1
	v_ashrrev_i32_e32 v1, 31, v0
	v_lshl_add_u64 v[34:35], s[74:75], 0, v[0:1]
	v_mad_u64_u32 v[36:37], s[8:9], v34, s14, v[38:39]
	v_lshlrev_b32_e32 v1, 4, v43
	v_add_u32_e32 v0, s18, v0
	v_mad_i32_i24 v37, v35, s14, v37
	v_and_b32_e32 v194, 0x70, v1
	v_ashrrev_i32_e32 v1, 31, v0
	v_lshl_add_u64 v[34:35], v[36:37], 0, s[92:93]
	v_lshlrev_b64 v[0:1], 13, v[0:1]
	v_lshl_add_u64 v[34:35], v[34:35], 0, v[194:195]
	s_mov_b64 s[8:9], 0x161c00
	v_lshl_add_u64 v[0:1], s[66:67], 0, v[0:1]
	v_lshl_add_u64 v[36:37], v[34:35], 0, s[8:9]
	v_lshl_add_u64 v[0:1], v[0:1], 0, v[194:195]
	s_mov_b64 s[8:9], 0x100
	v_lshl_add_u64 v[38:39], v[0:1], 0, s[8:9]
	s_mov_b64 s[8:9], 0x161c80
	global_load_lds_dwordx4 v[36:37], off
	v_lshl_add_u64 v[34:35], v[34:35], 0, s[8:9]
	s_mov_b32 m0, s73
	s_mov_b64 s[8:9], 0x80100
	global_load_lds_dwordx4 v[34:35], off
	s_mov_b32 m0, s89
	v_lshl_add_u64 v[0:1], v[0:1], 0, s[8:9]
	global_load_lds_dwordx4 v[38:39], off
	s_mov_b32 m0, s60
	v_max3_f32 v34, v18, v19, v20
	v_max3_f32 v35, v26, v27, v28
	s_and_b32 s9, s11, 0x380
	global_load_lds_dwordx4 v[0:1], off
	v_max3_f32 v0, v2, v3, v4
	v_max3_f32 v1, v10, v11, v12
	v_max3_f32 v34, v34, v21, v22
	v_max3_f32 v35, v35, v29, v30
	s_add_i32 s8, s35, 2
	v_max3_f32 v0, v0, v5, v6
	v_max3_f32 v1, v1, v13, v14
	v_max3_f32 v34, v34, v23, v24
	v_max3_f32 v35, v35, v31, v32
	s_nop 0
	v_max3_f32 v0, v0, v7, v8
	v_max3_f32 v1, v1, v15, v16
	s_nop 0
	v_max3_f32 v0, v0, v9, v1
	v_max3_f32 v1, v34, v25, v35
	s_nop 0
	v_max3_f32 v0, v0, v17, v33
	s_nop 0
	v_max3_f32 v0, v0, v1, v1
	s_nop 0
	v_mov_b32_e32 v1, v0
	s_nop 1
	v_permlane32_swap_b32_e32 v0, v1
	v_max3_f32 v0, v0, v1, v1
	s_nop 0
	v_max_f32_e32 v1, v0, v0
	v_max_f32_e32 v1, 0xf149f2ca, v1
	v_sub_f32_e32 v34, 0xf149f2ca, v1
	v_exp_f32_e32 v34, v34
	v_cmp_lt_f32_e32 vcc, s17, v0
	s_cmp_eq_u64 vcc, 0
	s_cselect_b64 vcc, -1, 0
	v_mul_f32_e32 v0, 0, v34
	v_cndmask_b32_e64 v0, v0, 0, vcc
	ds_read_b128 v[54:57], v40 offset:32768
	ds_read_b128 v[58:61], v40 offset:36864
	ds_read_b128 v[80:83], v41 offset:32768
	ds_read_b128 v[50:53], v41 offset:36864
	ds_read_b128 v[46:49], v42 offset:32768
	ds_read_b128 v[42:45], v42 offset:36864
	ds_read_b128 v[38:41], v62 offset:32768
	ds_read_b128 v[34:37], v62 offset:36864
	s_waitcnt lgkmcnt(0)
	v_mfma_f32_32x32x16_bf16 v[64:79], v[54:57], v[160:163], 0
	v_cndmask_b32_e32 v212, v1, v226, vcc
	v_mov_b32_e32 v213, v212
	v_pk_add_f32 v[2:3], v[2:3], v[212:213] neg_lo:[0,1] neg_hi:[0,1]
	v_pk_add_f32 v[18:19], v[18:19], v[212:213] neg_lo:[0,1] neg_hi:[0,1]
	v_pk_add_f32 v[4:5], v[4:5], v[212:213] neg_lo:[0,1] neg_hi:[0,1]
	v_pk_add_f32 v[20:21], v[20:21], v[212:213] neg_lo:[0,1] neg_hi:[0,1]
	v_pk_add_f32 v[6:7], v[6:7], v[212:213] neg_lo:[0,1] neg_hi:[0,1]
	v_mfma_f32_32x32x16_bf16 v[64:79], v[80:83], v[164:167], v[64:79]
	v_pk_add_f32 v[22:23], v[22:23], v[212:213] neg_lo:[0,1] neg_hi:[0,1]
	v_pk_add_f32 v[8:9], v[8:9], v[212:213] neg_lo:[0,1] neg_hi:[0,1]
	v_pk_add_f32 v[24:25], v[24:25], v[212:213] neg_lo:[0,1] neg_hi:[0,1]
	v_pk_add_f32 v[10:11], v[10:11], v[212:213] neg_lo:[0,1] neg_hi:[0,1]
	v_pk_add_f32 v[26:27], v[26:27], v[212:213] neg_lo:[0,1] neg_hi:[0,1]
	v_pk_add_f32 v[12:13], v[12:13], v[212:213] neg_lo:[0,1] neg_hi:[0,1]
	v_pk_add_f32 v[28:29], v[28:29], v[212:213] neg_lo:[0,1] neg_hi:[0,1]
	v_mfma_f32_32x32x16_bf16 v[80:95], v[58:61], v[160:163], 0
	v_pk_add_f32 v[14:15], v[14:15], v[212:213] neg_lo:[0,1] neg_hi:[0,1]
	v_pk_add_f32 v[30:31], v[30:31], v[212:213] neg_lo:[0,1] neg_hi:[0,1]
	v_pk_add_f32 v[16:17], v[16:17], v[212:213] neg_lo:[0,1] neg_hi:[0,1]
	v_pk_add_f32 v[32:33], v[32:33], v[212:213] neg_lo:[0,1] neg_hi:[0,1]
	v_exp_f32_e32 v2, v2
	v_exp_f32_e32 v18, v18
	v_exp_f32_e32 v3, v3
	v_mfma_f32_32x32x16_bf16 v[80:95], v[50:53], v[164:167], v[80:95]
	v_exp_f32_e32 v19, v19
	v_exp_f32_e32 v4, v4
	v_exp_f32_e32 v20, v20
	v_exp_f32_e32 v5, v5
	v_exp_f32_e32 v21, v21
	v_exp_f32_e32 v6, v6
	v_exp_f32_e32 v22, v22
	v_mfma_f32_32x32x16_bf16 v[64:79], v[46:49], v[168:171], v[64:79]
	v_exp_f32_e32 v7, v7
	v_exp_f32_e32 v23, v23
	v_exp_f32_e32 v8, v8
	v_exp_f32_e32 v24, v24
	v_exp_f32_e32 v9, v9
	v_exp_f32_e32 v25, v25
	v_exp_f32_e32 v10, v10
	v_mfma_f32_32x32x16_bf16 v[80:95], v[42:45], v[168:171], v[80:95]
	v_exp_f32_e32 v26, v26
	v_exp_f32_e32 v11, v11
	v_exp_f32_e32 v27, v27
	v_exp_f32_e32 v12, v12
	v_exp_f32_e32 v28, v28
	v_exp_f32_e32 v13, v13
	v_exp_f32_e32 v29, v29
	v_exp_f32_e32 v14, v14
	v_exp_f32_e32 v30, v30
	v_exp_f32_e32 v15, v15
	v_exp_f32_e32 v31, v31
	v_exp_f32_e32 v16, v16
	v_exp_f32_e32 v32, v32
	v_exp_f32_e32 v17, v17
	v_exp_f32_e32 v33, v33
	v_mfma_f32_32x32x16_bf16 v[64:79], v[38:41], v[172:175], v[64:79]
	v_add_f32_e64 v54, v12, v28
	v_add_f32_e64 v55, v13, v29
	v_add_f32_e64 v56, v4, v20
	v_add_f32_e64 v57, v5, v21
	v_add_f32_e64 v58, v16, v32
	v_add_f32_e64 v59, v17, v33
	v_pk_add_f32 v[60:61], v[8:9], v[24:25]
	v_pk_add_f32 v[62:63], v[10:11], v[26:27]
	v_pk_add_f32 v[96:97], v[2:3], v[18:19]
	v_pk_add_f32 v[98:99], v[14:15], v[30:31]
	v_mfma_f32_32x32x16_bf16 v[80:95], v[34:37], v[172:175], v[80:95]
	v_add_f32_e64 v100, v6, v22
	v_add_f32_e64 v101, v7, v23
	v_add_f32_e64 v62, v96, v62
	v_add_f32_e64 v63, v97, v63
	v_add_f32_e64 v98, v100, v98
	v_add_f32_e64 v99, v101, v99
	v_pk_add_f32 v[58:59], v[60:61], v[58:59]
	v_pk_add_f32 v[54:55], v[56:57], v[54:55]
	v_pk_add_f32 v[56:57], v[62:63], v[98:99]
	v_pk_add_f32 v[54:55], v[54:55], v[58:59]
	v_cvt_pk_bf16_f32 v96, v2, v3
	v_pk_mov_b32 v[58:59], v[56:57], v[54:55] op_sel:[1,0]
	v_mov_b32_e32 v57, v55
	v_pk_add_f32 v[54:55], v[58:59], v[56:57]
	v_cvt_pk_bf16_f32 v97, v4, v5
	v_add_f32_e32 v1, v54, v55
	v_cvt_pk_bf16_f32 v98, v6, v7
	v_cvt_pk_bf16_f32 v99, v8, v9
	v_cvt_pk_bf16_f32 v180, v18, v19
	v_cvt_pk_bf16_f32 v181, v20, v21
	v_cvt_pk_bf16_f32 v182, v22, v23
	v_cvt_pk_bf16_f32 v183, v24, v25
	v_cvt_pk_bf16_f32 v184, v10, v11
	v_cvt_pk_bf16_f32 v185, v12, v13
	v_cvt_pk_bf16_f32 v186, v14, v15
	v_cvt_pk_bf16_f32 v187, v16, v17
	v_cvt_pk_bf16_f32 v176, v26, v27
	v_cvt_pk_bf16_f32 v177, v28, v29
	v_cvt_pk_bf16_f32 v178, v30, v31
	v_cvt_pk_bf16_f32 v179, v32, v33
	v_add_f32_e32 v100, v0, v1
	v_mov_b32_e32 v14, v0
	v_mov_b32_e32 v15, v0
	v_mov_b32_e32 v1, v0
	v_mov_b32_e32 v2, v0
	v_mov_b32_e32 v3, v0
	v_mov_b32_e32 v4, v0
	v_mov_b32_e32 v5, v0
	v_mov_b32_e32 v6, v0
	v_mov_b32_e32 v7, v0
	v_mov_b32_e32 v8, v0
	v_mov_b32_e32 v9, v0
	v_mov_b32_e32 v10, v0
	v_mov_b32_e32 v11, v0
	v_mov_b32_e32 v12, v0
	v_mov_b32_e32 v13, v0
	v_lshlrev_b32_e32 v232, 2, v215
	v_readlane_b32 s40, v255, 45
	v_mov_b64_e32 v[62:63], v[14:15]
	v_mov_b64_e32 v[46:47], v[14:15]
	v_mov_b64_e32 v[30:31], v[14:15]
	v_add_u32_e32 v237, 0, v227
	v_subrev_u32_e32 v208, s0, v232
	s_or_b32 s17, s1, s9
	v_readlane_b32 s41, v255, 46
	v_mov_b64_e32 v[60:61], v[12:13]
	v_mov_b64_e32 v[58:59], v[10:11]
	v_mov_b64_e32 v[56:57], v[8:9]
	v_mov_b64_e32 v[54:55], v[6:7]
	v_mov_b64_e32 v[52:53], v[4:5]
	v_mov_b64_e32 v[50:51], v[2:3]
	v_mov_b64_e32 v[48:49], v[0:1]
	v_mov_b64_e32 v[44:45], v[12:13]
	v_mov_b64_e32 v[42:43], v[10:11]
	v_mov_b64_e32 v[40:41], v[8:9]
	v_mov_b64_e32 v[38:39], v[6:7]
	v_mov_b64_e32 v[36:37], v[4:5]
	v_mov_b64_e32 v[34:35], v[2:3]
	v_mov_b64_e32 v[32:33], v[0:1]
	v_mov_b64_e32 v[28:29], v[12:13]
	v_mov_b64_e32 v[26:27], v[10:11]
	v_mov_b64_e32 v[24:25], v[8:9]
	v_mov_b64_e32 v[22:23], v[6:7]
	v_mov_b64_e32 v[20:21], v[4:5]
	v_mov_b64_e32 v[18:19], v[2:3]
	v_mov_b64_e32 v[16:17], v[0:1]
	s_waitcnt vmcnt(2)
	s_barrier

.LBB0_836:
	s_add_i32 s79, s10, 2
	s_cmp_ge_u32 s79, s8
	s_cselect_b64 s[76:77], -1, 0
	s_and_b64 vcc, exec, s[76:77]
	s_waitcnt vmcnt(2)
	s_barrier
	s_cbranch_vccnz .LBB0_838
	v_mov_b32_e32 v76, v233
	s_add_u32 s0, s74, s38
	v_ashrrev_i32_e32 v70, 3, v76
	v_ashrrev_i32_e32 v71, 31, v70
	s_addc_u32 s1, s75, s39
	v_lshl_add_u64 v[72:73], s[0:1], 0, v[70:71]
	s_mov_b64 s[0:1], 0x100
	v_lshl_add_u64 v[72:73], v[72:73], 0, s[0:1]
	v_mov_b64_e32 v[74:75], s[82:83]
	v_mad_u64_u32 v[74:75], s[0:1], v72, s14, v[74:75]
	v_lshrrev_b32_e32 v77, 4, v76
	v_mov_b32_e32 v68, v75
	v_xor_b32_e32 v78, v77, v76
	v_mad_u64_u32 v[72:73], s[0:1], v73, s14, v[68:69]
	v_mov_b32_e32 v75, v72
	s_lshl_b32 s92, s46, 1
	v_lshlrev_b32_e32 v68, 4, v78
	v_add_u32_e32 v70, s17, v70
	v_lshl_add_u64 v[72:73], v[74:75], 0, s[92:93]
	v_and_b32_e32 v194, 0x70, v68
	v_ashrrev_i32_e32 v71, 31, v70
	v_lshl_add_u64 v[72:73], v[72:73], 0, v[194:195]
	v_lshlrev_b64 v[70:71], 13, v[70:71]
	v_bitop3_b32 v68, v77, 7, v76 bitop3:0x48
	s_add_i32 s0, s5, s33
	v_lshl_add_u64 v[74:75], v[72:73], 0, s[30:31]
	v_lshl_or_b32 v70, v68, 4, v70
	s_mov_b32 m0, s0
	v_lshl_add_u64 v[70:71], s[40:41], 0, v[70:71]
	global_load_lds_dwordx4 v[74:75], off
	v_lshl_add_u64 v[72:73], v[72:73], 0, s[42:43]
	s_add_i32 m0, s0, 0x2000
	v_lshl_add_u64 v[76:77], v[70:71], 0, s[48:49]
	global_load_lds_dwordx4 v[72:73], off
	s_add_i32 m0, s0, 0x4000
	v_lshl_add_u64 v[70:71], v[70:71], 0, s[96:97]
	global_load_lds_dwordx4 v[76:77], off
	s_add_i32 m0, s0, 0x6000
	s_nop 0
	global_load_lds_dwordx4 v[70:71], off

.LBB0_842:
	s_add_u32 s38, s38, 0x80
	s_addc_u32 s39, s39, 0
	s_add_u32 s40, s40, 0x100
	s_addc_u32 s41, s41, 0
	s_and_b64 vcc, exec, s[76:77]
	s_waitcnt vmcnt(2)
	s_barrier
	s_cbranch_vccnz .LBB0_844
	s_mov_b32 s78, s9
	s_mov_b32 s10, s79
	s_branch .LBB0_830

.LBB0_846:
	v_readlane_b32 s0, v254, 38
	v_readlane_b32 s1, v254, 39
	v_lshrrev_b32_e32 v156, 4, v234
	s_andn2_b64 vcc, exec, s[0:1]
	v_cndmask_b32_e64 v64, 0, 1, s[0:1]
	v_cmp_ne_u32_e64 s[38:39], 1, v64
	v_lshlrev_b32_e32 v64, 4, v233
	v_and_b32_e32 v194, 0xf0, v64
	v_or_b32_e32 v113, s7, v156
	s_mul_i32 s0, s65, 0x2c00
	s_waitcnt vmcnt(0)
	s_barrier
	s_cbranch_vccnz .LBB0_848
	s_lshl_b32 s1, s46, 1
	s_add_u32 s34, s82, s1
	s_addc_u32 s35, s83, 0
	v_lshl_add_u64 v[64:65], s[34:35], 0, v[194:195]
	v_mad_u64_u32 v[66:67], s[34:35], v113, s14, v[64:65]
	v_add_u32_e32 v67, s0, v67
	v_add_co_u32_e32 v66, vcc, s4, v66
	v_or_b32_e32 v68, 4, v113
	s_nop 0
	v_addc_co_u32_e32 v67, vcc, 0, v67, vcc
	v_mad_u64_u32 v[68:69], s[34:35], v68, s14, v[64:65]
	v_add_u32_e32 v69, s0, v69
	v_add_co_u32_e32 v68, vcc, s4, v68
	s_nop 1
	v_addc_co_u32_e32 v69, vcc, 0, v69, vcc
	global_load_dwordx4 v[92:95], v[66:67], off offset:1024
	global_load_dwordx4 v[88:91], v[68:69], off offset:1024
	v_or_b32_e32 v66, 8, v113
	v_mad_u64_u32 v[66:67], s[34:35], v66, s14, v[64:65]
	v_add_u32_e32 v67, s0, v67
	v_add_co_u32_e32 v66, vcc, s4, v66
	v_or_b32_e32 v68, 12, v113
	s_nop 0
	v_addc_co_u32_e32 v67, vcc, 0, v67, vcc
	v_mad_u64_u32 v[68:69], s[34:35], v68, s14, v[64:65]
	v_add_u32_e32 v69, s0, v69
	v_add_co_u32_e32 v68, vcc, s4, v68
	s_nop 1
	v_addc_co_u32_e32 v69, vcc, 0, v69, vcc
	global_load_dwordx4 v[84:87], v[66:67], off offset:1024
	global_load_dwordx4 v[80:83], v[68:69], off offset:1024
	v_or_b32_e32 v66, 16, v113
	v_mad_u64_u32 v[66:67], s[34:35], v66, s14, v[64:65]
	v_add_u32_e32 v67, s0, v67
	v_add_co_u32_e32 v66, vcc, s4, v66
	v_or_b32_e32 v68, 20, v113
	s_nop 0
	v_addc_co_u32_e32 v67, vcc, 0, v67, vcc
	v_mad_u64_u32 v[68:69], s[34:35], v68, s14, v[64:65]
	v_add_u32_e32 v69, s0, v69
	v_add_co_u32_e32 v68, vcc, s4, v68
	s_nop 1
	v_addc_co_u32_e32 v69, vcc, 0, v69, vcc
	global_load_dwordx4 v[76:79], v[66:67], off offset:1024
	global_load_dwordx4 v[72:75], v[68:69], off offset:1024
	v_or_b32_e32 v66, 24, v113
	v_mad_u64_u32 v[66:67], s[34:35], v66, s14, v[64:65]
	v_add_u32_e32 v67, s0, v67
	v_add_co_u32_e32 v66, vcc, s4, v66
	v_or_b32_e32 v68, 28, v113
	s_nop 0
	v_addc_co_u32_e32 v67, vcc, 0, v67, vcc
	v_mad_u64_u32 v[64:65], s[34:35], v68, s14, v[64:65]
	v_add_u32_e32 v65, s0, v65
	v_add_co_u32_e32 v64, vcc, s4, v64
	s_nop 1
	v_addc_co_u32_e32 v65, vcc, 0, v65, vcc
	global_load_dwordx4 v[68:71], v[66:67], off offset:1024
	s_nop 0
	global_load_dwordx4 v[64:67], v[64:65], off offset:1024

.LBB0_858:
	v_max3_f32 v0, v2, v3, v4
	v_max3_f32 v37, v10, v11, v12
	v_max3_f32 v38, v18, v19, v20
	v_max3_f32 v39, v26, v27, v28
	s_mov_b32 s9, 0xf149f2ca
	v_max3_f32 v0, v0, v5, v6
	v_max3_f32 v37, v37, v13, v14
	v_max3_f32 v38, v38, v21, v22
	v_max3_f32 v39, v39, v29, v30
	s_lshl_b32 s8, s16, 1
	v_max3_f32 v0, v0, v7, v8
	v_max3_f32 v37, v37, v15, v16
	v_max3_f32 v38, v38, v23, v24
	v_max3_f32 v39, v39, v31, v32
	s_nop 0
	v_max3_f32 v0, v0, v9, v37
	v_max3_f32 v37, v38, v25, v39
	s_nop 0
	v_max3_f32 v0, v0, v17, v33
	s_nop 0
	v_max3_f32 v0, v0, v37, v37
	s_nop 0
	v_mov_b32_e32 v37, v0
	s_nop 1
	v_permlane32_swap_b32_e32 v0, v37
	v_max3_f32 v0, v0, v37, v37
	s_nop 0
	v_max_f32_e32 v37, v0, v0
	v_max_f32_e32 v62, 0xf149f2ca, v37
	v_sub_f32_e32 v37, 0xf149f2ca, v62
	v_exp_f32_e32 v37, v37
	v_cmp_lt_f32_e32 vcc, s9, v0
	s_cmp_eq_u64 vcc, 0
	s_cselect_b64 vcc, -1, 0
	v_mul_f32_e32 v0, 0, v37
	v_cndmask_b32_e64 v0, v0, 0, vcc
	ds_read_b128 v[54:57], v1 offset:32768
	ds_read_b128 v[58:61], v1 offset:36864
	ds_read_b128 v[80:83], v34 offset:32768
	ds_read_b128 v[50:53], v34 offset:36864
	ds_read_b128 v[46:49], v35 offset:32768
	ds_read_b128 v[42:45], v35 offset:36864
	ds_read_b128 v[38:41], v36 offset:32768
	ds_read_b128 v[34:37], v36 offset:36864
	s_waitcnt lgkmcnt(0)
	v_mfma_f32_32x32x16_bf16 v[64:79], v[54:57], v[160:163], 0
	v_cndmask_b32_e32 v214, v62, v226, vcc
	v_mov_b32_e32 v215, v214
	v_pk_add_f32 v[2:3], v[2:3], v[214:215] neg_lo:[0,1] neg_hi:[0,1]
	v_pk_add_f32 v[18:19], v[18:19], v[214:215] neg_lo:[0,1] neg_hi:[0,1]
	v_pk_add_f32 v[4:5], v[4:5], v[214:215] neg_lo:[0,1] neg_hi:[0,1]
	v_pk_add_f32 v[20:21], v[20:21], v[214:215] neg_lo:[0,1] neg_hi:[0,1]
	v_pk_add_f32 v[6:7], v[6:7], v[214:215] neg_lo:[0,1] neg_hi:[0,1]
	v_mfma_f32_32x32x16_bf16 v[64:79], v[80:83], v[164:167], v[64:79]
	v_pk_add_f32 v[22:23], v[22:23], v[214:215] neg_lo:[0,1] neg_hi:[0,1]
	v_pk_add_f32 v[8:9], v[8:9], v[214:215] neg_lo:[0,1] neg_hi:[0,1]
	v_pk_add_f32 v[24:25], v[24:25], v[214:215] neg_lo:[0,1] neg_hi:[0,1]
	v_pk_add_f32 v[10:11], v[10:11], v[214:215] neg_lo:[0,1] neg_hi:[0,1]
	v_pk_add_f32 v[26:27], v[26:27], v[214:215] neg_lo:[0,1] neg_hi:[0,1]
	v_pk_add_f32 v[12:13], v[12:13], v[214:215] neg_lo:[0,1] neg_hi:[0,1]
	v_pk_add_f32 v[28:29], v[28:29], v[214:215] neg_lo:[0,1] neg_hi:[0,1]
	v_mfma_f32_32x32x16_bf16 v[80:95], v[58:61], v[160:163], 0
	v_pk_add_f32 v[14:15], v[14:15], v[214:215] neg_lo:[0,1] neg_hi:[0,1]
	v_pk_add_f32 v[30:31], v[30:31], v[214:215] neg_lo:[0,1] neg_hi:[0,1]
	v_pk_add_f32 v[16:17], v[16:17], v[214:215] neg_lo:[0,1] neg_hi:[0,1]
	v_pk_add_f32 v[32:33], v[32:33], v[214:215] neg_lo:[0,1] neg_hi:[0,1]
	v_exp_f32_e32 v2, v2
	v_exp_f32_e32 v18, v18
	v_exp_f32_e32 v3, v3
	v_mfma_f32_32x32x16_bf16 v[80:95], v[50:53], v[164:167], v[80:95]
	v_exp_f32_e32 v19, v19
	v_exp_f32_e32 v4, v4
	v_exp_f32_e32 v20, v20
	v_exp_f32_e32 v5, v5
	v_exp_f32_e32 v21, v21
	v_exp_f32_e32 v6, v6
	v_exp_f32_e32 v22, v22
	v_mfma_f32_32x32x16_bf16 v[64:79], v[46:49], v[168:171], v[64:79]
	v_exp_f32_e32 v7, v7
	v_exp_f32_e32 v23, v23
	v_exp_f32_e32 v8, v8
	v_exp_f32_e32 v24, v24
	v_exp_f32_e32 v9, v9
	v_exp_f32_e32 v25, v25
	v_exp_f32_e32 v10, v10
	v_mfma_f32_32x32x16_bf16 v[80:95], v[42:45], v[168:171], v[80:95]
	v_exp_f32_e32 v26, v26
	v_exp_f32_e32 v11, v11
	v_exp_f32_e32 v27, v27
	v_exp_f32_e32 v12, v12
	v_exp_f32_e32 v28, v28
	v_exp_f32_e32 v13, v13
	v_exp_f32_e32 v29, v29
	v_exp_f32_e32 v14, v14
	v_exp_f32_e32 v30, v30
	v_exp_f32_e32 v15, v15
	v_exp_f32_e32 v31, v31
	v_exp_f32_e32 v16, v16
	v_exp_f32_e32 v32, v32
	v_exp_f32_e32 v17, v17
	v_exp_f32_e32 v33, v33
	v_mfma_f32_32x32x16_bf16 v[64:79], v[38:41], v[172:175], v[64:79]
	v_add_f32_e64 v54, v12, v28
	v_add_f32_e64 v55, v13, v29
	v_add_f32_e64 v56, v4, v20
	v_add_f32_e64 v57, v5, v21
	v_add_f32_e64 v58, v16, v32
	v_add_f32_e64 v59, v17, v33
	v_pk_add_f32 v[60:61], v[8:9], v[24:25]
	v_pk_add_f32 v[62:63], v[10:11], v[26:27]
	v_pk_add_f32 v[96:97], v[2:3], v[18:19]
	v_pk_add_f32 v[98:99], v[14:15], v[30:31]
	v_mfma_f32_32x32x16_bf16 v[80:95], v[34:37], v[172:175], v[80:95]
	v_add_f32_e64 v100, v6, v22
	v_add_f32_e64 v101, v7, v23
	v_add_f32_e64 v62, v96, v62
	v_add_f32_e64 v63, v97, v63
	v_add_f32_e64 v98, v100, v98
	v_add_f32_e64 v99, v101, v99
	v_pk_add_f32 v[58:59], v[60:61], v[58:59]
	v_pk_add_f32 v[54:55], v[56:57], v[54:55]
	v_pk_add_f32 v[56:57], v[62:63], v[98:99]
	v_pk_add_f32 v[54:55], v[54:55], v[58:59]
	v_cvt_pk_bf16_f32 v96, v2, v3
	v_pk_mov_b32 v[58:59], v[56:57], v[54:55] op_sel:[1,0]
	v_mov_b32_e32 v57, v55
	v_pk_add_f32 v[54:55], v[58:59], v[56:57]
	v_cvt_pk_bf16_f32 v97, v4, v5
	v_add_f32_e32 v1, v54, v55
	v_cvt_pk_bf16_f32 v98, v6, v7
	v_cvt_pk_bf16_f32 v99, v8, v9
	v_cvt_pk_bf16_f32 v180, v18, v19
	v_cvt_pk_bf16_f32 v181, v20, v21
	v_cvt_pk_bf16_f32 v182, v22, v23
	v_cvt_pk_bf16_f32 v183, v24, v25
	v_cvt_pk_bf16_f32 v184, v10, v11
	v_cvt_pk_bf16_f32 v185, v12, v13
	v_cvt_pk_bf16_f32 v186, v14, v15
	v_cvt_pk_bf16_f32 v187, v16, v17
	v_cvt_pk_bf16_f32 v176, v26, v27
	v_cvt_pk_bf16_f32 v177, v28, v29
	v_cvt_pk_bf16_f32 v178, v30, v31
	v_cvt_pk_bf16_f32 v179, v32, v33
	v_add_f32_e32 v100, v0, v1
	v_mov_b32_e32 v1, v0
	v_mov_b32_e32 v2, v0
	v_mov_b32_e32 v3, v0
	v_mov_b32_e32 v4, v0
	v_mov_b32_e32 v5, v0
	v_mov_b32_e32 v6, v0
	v_mov_b32_e32 v7, v0
	v_mov_b32_e32 v8, v0
	v_mov_b32_e32 v9, v0
	v_mov_b32_e32 v10, v0
	v_mov_b32_e32 v11, v0
	v_mov_b32_e32 v12, v0
	v_mov_b32_e32 v13, v0
	v_mov_b32_e32 v14, v0
	v_mov_b32_e32 v15, v0
	s_andn2_b64 vcc, exec, s[0:1]
	s_waitcnt vmcnt(2)
	s_barrier
	s_cbranch_vccnz .LBB0_874
	s_and_b32 s0, s3, 15
	s_lshl_b32 s0, s0, 7
	v_readlane_b32 s76, v255, 45
	v_mov_b64_e32 v[62:63], v[14:15]
	v_mov_b64_e32 v[46:47], v[14:15]
	v_mov_b64_e32 v[30:31], v[14:15]
	s_mov_b32 s35, 2
	s_add_i32 s18, s8, 2
	v_add_u32_e32 v237, 0, v229
	v_subrev_u32_e32 v208, s0, v212
	s_mov_b64 s[64:65], 0
	s_mov_b32 s34, 0x10000
	v_readlane_b32 s77, v255, 46
	v_mov_b64_e32 v[60:61], v[12:13]
	v_mov_b64_e32 v[58:59], v[10:11]
	v_mov_b64_e32 v[56:57], v[8:9]
	v_mov_b64_e32 v[54:55], v[6:7]
	v_mov_b64_e32 v[52:53], v[4:5]
	v_mov_b64_e32 v[50:51], v[2:3]
	v_mov_b64_e32 v[48:49], v[0:1]
	v_mov_b64_e32 v[44:45], v[12:13]
	v_mov_b64_e32 v[42:43], v[10:11]
	v_mov_b64_e32 v[40:41], v[8:9]
	v_mov_b64_e32 v[38:39], v[6:7]
	v_mov_b64_e32 v[36:37], v[4:5]
	v_mov_b64_e32 v[34:35], v[2:3]
	v_mov_b64_e32 v[32:33], v[0:1]
	v_mov_b64_e32 v[28:29], v[12:13]
	v_mov_b64_e32 v[26:27], v[10:11]
	v_mov_b64_e32 v[24:25], v[8:9]
	v_mov_b64_e32 v[22:23], v[6:7]
	v_mov_b64_e32 v[20:21], v[4:5]
	v_mov_b64_e32 v[18:19], v[2:3]
	v_mov_b64_e32 v[16:17], v[0:1]

.LBB0_866:
	s_add_i32 s10, s35, 2
	s_cmp_ge_u32 s10, s18
	s_cselect_b64 s[90:91], -1, 0
	s_and_b64 vcc, exec, s[90:91]
	s_waitcnt vmcnt(2)
	s_barrier
	s_cbranch_vccnz .LBB0_868
	v_mov_b32_e32 v76, v234
	s_add_u32 s0, s74, s64
	v_ashrrev_i32_e32 v70, 3, v76
	v_ashrrev_i32_e32 v71, 31, v70
	s_addc_u32 s1, s75, s65
	v_lshl_add_u64 v[72:73], s[0:1], 0, v[70:71]
	s_mov_b64 s[0:1], 0x100
	v_lshl_add_u64 v[72:73], v[72:73], 0, s[0:1]
	v_mov_b64_e32 v[74:75], s[82:83]
	v_mad_u64_u32 v[74:75], s[0:1], v72, s14, v[74:75]
	v_lshrrev_b32_e32 v77, 4, v76
	v_mov_b32_e32 v68, v75
	v_xor_b32_e32 v78, v77, v76
	v_mad_u64_u32 v[72:73], s[0:1], v73, s14, v[68:69]
	v_mov_b32_e32 v75, v72
	v_lshlrev_b32_e32 v68, 4, v78
	v_add_u32_e32 v70, s17, v70
	v_lshl_add_u64 v[72:73], v[74:75], 0, s[92:93]
	v_and_b32_e32 v194, 0x70, v68
	v_ashrrev_i32_e32 v71, 31, v70
	v_lshl_add_u64 v[72:73], v[72:73], 0, v[194:195]
	v_lshlrev_b64 v[70:71], 13, v[70:71]
	v_bitop3_b32 v68, v77, 7, v76 bitop3:0x48
	s_add_i32 s0, s5, s33
	v_lshl_add_u64 v[74:75], v[72:73], 0, s[30:31]
	v_lshl_or_b32 v70, v68, 4, v70
	s_mov_b32 m0, s0
	v_lshl_add_u64 v[70:71], s[76:77], 0, v[70:71]
	global_load_lds_dwordx4 v[74:75], off
	v_lshl_add_u64 v[72:73], v[72:73], 0, s[42:43]
	s_add_i32 m0, s0, 0x2000
	v_lshl_add_u64 v[76:77], v[70:71], 0, s[48:49]
	global_load_lds_dwordx4 v[72:73], off
	s_add_i32 m0, s0, 0x4000
	v_lshl_add_u64 v[70:71], v[70:71], 0, s[96:97]
	global_load_lds_dwordx4 v[76:77], off
	s_add_i32 m0, s0, 0x6000
	s_nop 0
	global_load_lds_dwordx4 v[70:71], off

.LBB0_872:
	s_add_u32 s64, s64, 0x80
	s_addc_u32 s65, s65, 0
	s_add_u32 s76, s76, 0x100
	s_addc_u32 s77, s77, 0
	s_and_b64 vcc, exec, s[90:91]
	s_waitcnt vmcnt(2)
	s_barrier
	s_cbranch_vccnz .LBB0_875
	s_mov_b32 s34, s9
	s_mov_b32 s35, s10
	s_branch .LBB0_860

.LBB0_877:
	v_lshlrev_b32_e32 v64, 4, v234
	v_lshrrev_b32_e32 v158, 4, v112
	s_and_b64 vcc, exec, s[38:39]
	v_and_b32_e32 v194, 0xf0, v64
	v_or_b32_e32 v113, s7, v158
	s_mul_i32 s0, s75, 0x2c00
	s_waitcnt vmcnt(0)
	s_barrier
	s_cbranch_vccnz .LBB0_879
	s_add_u32 s16, s82, s92
	s_addc_u32 s17, s83, 0
	v_lshl_add_u64 v[64:65], s[16:17], 0, v[194:195]
	v_mad_u64_u32 v[66:67], s[16:17], v113, s14, v[64:65]
	v_add_u32_e32 v67, s0, v67
	v_add_co_u32_e32 v66, vcc, s4, v66
	v_or_b32_e32 v68, 4, v113
	s_nop 0
	v_addc_co_u32_e32 v67, vcc, 0, v67, vcc
	v_mad_u64_u32 v[68:69], s[16:17], v68, s14, v[64:65]
	v_add_u32_e32 v69, s0, v69
	v_add_co_u32_e32 v68, vcc, s4, v68
	s_nop 1
	v_addc_co_u32_e32 v69, vcc, 0, v69, vcc
	global_load_dwordx4 v[92:95], v[66:67], off offset:1024
	global_load_dwordx4 v[88:91], v[68:69], off offset:1024
	v_or_b32_e32 v66, 8, v113
	v_mad_u64_u32 v[66:67], s[16:17], v66, s14, v[64:65]
	v_add_u32_e32 v67, s0, v67
	v_add_co_u32_e32 v66, vcc, s4, v66
	v_or_b32_e32 v68, 12, v113
	s_nop 0
	v_addc_co_u32_e32 v67, vcc, 0, v67, vcc
	v_mad_u64_u32 v[68:69], s[16:17], v68, s14, v[64:65]
	v_add_u32_e32 v69, s0, v69
	v_add_co_u32_e32 v68, vcc, s4, v68
	s_nop 1
	v_addc_co_u32_e32 v69, vcc, 0, v69, vcc
	global_load_dwordx4 v[84:87], v[66:67], off offset:1024
	global_load_dwordx4 v[80:83], v[68:69], off offset:1024
	v_or_b32_e32 v66, 16, v113
	v_mad_u64_u32 v[66:67], s[16:17], v66, s14, v[64:65]
	v_add_u32_e32 v67, s0, v67
	v_add_co_u32_e32 v66, vcc, s4, v66
	v_or_b32_e32 v68, 20, v113
	s_nop 0
	v_addc_co_u32_e32 v67, vcc, 0, v67, vcc
	v_mad_u64_u32 v[68:69], s[16:17], v68, s14, v[64:65]
	v_add_u32_e32 v69, s0, v69
	v_add_co_u32_e32 v68, vcc, s4, v68
	s_nop 1
	v_addc_co_u32_e32 v69, vcc, 0, v69, vcc
	global_load_dwordx4 v[76:79], v[66:67], off offset:1024
	global_load_dwordx4 v[72:75], v[68:69], off offset:1024
	v_or_b32_e32 v66, 24, v113
	v_mad_u64_u32 v[66:67], s[16:17], v66, s14, v[64:65]
	v_add_u32_e32 v67, s0, v67
	v_add_co_u32_e32 v66, vcc, s4, v66
	v_or_b32_e32 v68, 28, v113
	s_nop 0
	v_addc_co_u32_e32 v67, vcc, 0, v67, vcc
	v_mad_u64_u32 v[64:65], s[16:17], v68, s14, v[64:65]
	v_add_u32_e32 v65, s0, v65
	v_add_co_u32_e32 v64, vcc, s4, v64
	s_nop 1
	v_addc_co_u32_e32 v65, vcc, 0, v65, vcc
	global_load_dwordx4 v[68:71], v[66:67], off offset:1024
	s_nop 0
	global_load_dwordx4 v[64:67], v[64:65], off offset:1024
